# phase 0 activation conversion (cvt_rows): software-pipelined fast path with 16 loads in flight per thread for the frozen 256x512 launch, original loop kept as general path
# speedup vs baseline: 1.0040x; 1.0040x over previous
.LBB0_74:
	v_readlane_b32 s19, v253, 0
	s_mov_b32 s18, s19
	s_mov_b32 s26, s19
	s_ashr_i32 s27, s26, 31
	s_waitcnt lgkmcnt(1)
	v_mov_b32_e32 v2, v230
	s_lshl_b64 s[18:19], s[26:27], 12
	s_waitcnt lgkmcnt(0)
	v_ashrrev_i32_e32 v3, 31, v2
	v_lshl_add_u64 v[0:1], v[2:3], 3, s[18:19]
	s_mov_b64 s[18:19], 0x1000000
	v_cmp_gt_u64_e32 vcc, s[18:19], v[0:1]
	v_lshlrev_b64 v[4:5], 5, v[2:3]
	s_and_saveexec_b64 s[28:29], vcc
	s_cbranch_execz .LBB0_77
	s_lshl_b64 s[18:19], s[26:27], 14
	v_readlane_b32 s30, v254, 46
	s_add_u32 s18, s30, s18
	v_readlane_b32 s30, v254, 62
	s_addc_u32 s19, s30, s19
	v_lshl_add_u64 v[16:17], s[18:19], 0, v[4:5]
	s_lshl_b64 s[18:19], s[26:27], 13
	v_readlane_b32 s30, v255, 0
	s_add_u32 s18, s30, s18
	v_readlane_b32 s30, v255, 2
	s_addc_u32 s19, s30, s19
	v_lshl_add_u64 v[18:19], v[2:3], 4, s[18:19]
	s_mov_b64 s[18:19], 0
	v_mov_b64_e32 v[20:21], v[0:1]
	s_cmp_lg_u32 s22, 0x100000
	s_cbranch_scc1 .LBB0_76
	s_cmp_lg_u32 s23, 0
	s_cbranch_scc1 .LBB0_76
	global_load_dwordx4 v[24:27], v[16:17], off offset:-16
	global_load_dwordx4 v[28:31], v[16:17], off
	v_lshl_add_u64 v[16:17], v[16:17], 0, s[90:91]
	global_load_dwordx4 v[138:141], v[16:17], off offset:-16
	global_load_dwordx4 v[142:145], v[16:17], off
	v_lshl_add_u64 v[16:17], v[16:17], 0, s[90:91]
	global_load_dwordx4 v[146:149], v[16:17], off offset:-16
	global_load_dwordx4 v[150:153], v[16:17], off
	v_lshl_add_u64 v[16:17], v[16:17], 0, s[90:91]
	global_load_dwordx4 v[154:157], v[16:17], off offset:-16
	global_load_dwordx4 v[158:161], v[16:17], off
	v_lshl_add_u64 v[16:17], v[16:17], 0, s[90:91]
	global_load_dwordx4 v[162:165], v[16:17], off offset:-16
	global_load_dwordx4 v[194:197], v[16:17], off
	v_lshl_add_u64 v[16:17], v[16:17], 0, s[90:91]
	global_load_dwordx4 v[198:201], v[16:17], off offset:-16
	global_load_dwordx4 v[202:205], v[16:17], off
	v_lshl_add_u64 v[16:17], v[16:17], 0, s[90:91]
	global_load_dwordx4 v[206:209], v[16:17], off offset:-16
	global_load_dwordx4 v[210:213], v[16:17], off
	v_lshl_add_u64 v[16:17], v[16:17], 0, s[90:91]
	global_load_dwordx4 v[110:113], v[16:17], off offset:-16
	global_load_dwordx4 v[114:117], v[16:17], off
	v_lshl_add_u64 v[16:17], v[16:17], 0, s[90:91]
	s_waitcnt vmcnt(14)
	v_cvt_pk_bf16_f32 v24, v24, v25
	v_cvt_pk_bf16_f32 v25, v26, v27
	v_cvt_pk_bf16_f32 v26, v28, v29
	v_cvt_pk_bf16_f32 v27, v30, v31
	global_store_dwordx4 v[18:19], v[24:27], off
	v_lshl_add_u64 v[18:19], v[18:19], 0, s[92:93]
	s_nop 0
	global_load_dwordx4 v[24:27], v[16:17], off offset:-16
	global_load_dwordx4 v[28:31], v[16:17], off
	v_lshl_add_u64 v[16:17], v[16:17], 0, s[90:91]
	s_waitcnt vmcnt(15)
	v_cvt_pk_bf16_f32 v138, v138, v139
	v_cvt_pk_bf16_f32 v139, v140, v141
	v_cvt_pk_bf16_f32 v140, v142, v143
	v_cvt_pk_bf16_f32 v141, v144, v145
	global_store_dwordx4 v[18:19], v[138:141], off
	v_lshl_add_u64 v[18:19], v[18:19], 0, s[92:93]
	s_nop 0
	global_load_dwordx4 v[138:141], v[16:17], off offset:-16
	global_load_dwordx4 v[142:145], v[16:17], off
	v_lshl_add_u64 v[16:17], v[16:17], 0, s[90:91]
	s_waitcnt vmcnt(16)
	v_cvt_pk_bf16_f32 v146, v146, v147
	v_cvt_pk_bf16_f32 v147, v148, v149
	v_cvt_pk_bf16_f32 v148, v150, v151
	v_cvt_pk_bf16_f32 v149, v152, v153
	global_store_dwordx4 v[18:19], v[146:149], off
	v_lshl_add_u64 v[18:19], v[18:19], 0, s[92:93]
	s_nop 0
	global_load_dwordx4 v[146:149], v[16:17], off offset:-16
	global_load_dwordx4 v[150:153], v[16:17], off
	v_lshl_add_u64 v[16:17], v[16:17], 0, s[90:91]
	s_waitcnt vmcnt(17)
	v_cvt_pk_bf16_f32 v154, v154, v155
	v_cvt_pk_bf16_f32 v155, v156, v157
	v_cvt_pk_bf16_f32 v156, v158, v159
	v_cvt_pk_bf16_f32 v157, v160, v161
	global_store_dwordx4 v[18:19], v[154:157], off
	v_lshl_add_u64 v[18:19], v[18:19], 0, s[92:93]
	s_nop 0
	global_load_dwordx4 v[154:157], v[16:17], off offset:-16
	global_load_dwordx4 v[158:161], v[16:17], off
	v_lshl_add_u64 v[16:17], v[16:17], 0, s[90:91]
	s_waitcnt vmcnt(18)
	v_cvt_pk_bf16_f32 v162, v162, v163
	v_cvt_pk_bf16_f32 v163, v164, v165
	v_cvt_pk_bf16_f32 v164, v194, v195
	v_cvt_pk_bf16_f32 v165, v196, v197
	global_store_dwordx4 v[18:19], v[162:165], off
	v_lshl_add_u64 v[18:19], v[18:19], 0, s[92:93]
	s_nop 0
	global_load_dwordx4 v[162:165], v[16:17], off offset:-16
	global_load_dwordx4 v[194:197], v[16:17], off
	v_lshl_add_u64 v[16:17], v[16:17], 0, s[90:91]
	s_waitcnt vmcnt(19)
	v_cvt_pk_bf16_f32 v198, v198, v199
	v_cvt_pk_bf16_f32 v199, v200, v201
	v_cvt_pk_bf16_f32 v200, v202, v203
	v_cvt_pk_bf16_f32 v201, v204, v205
	global_store_dwordx4 v[18:19], v[198:201], off
	v_lshl_add_u64 v[18:19], v[18:19], 0, s[92:93]
	s_nop 0
	global_load_dwordx4 v[198:201], v[16:17], off offset:-16
	global_load_dwordx4 v[202:205], v[16:17], off
	v_lshl_add_u64 v[16:17], v[16:17], 0, s[90:91]
	s_waitcnt vmcnt(20)
	v_cvt_pk_bf16_f32 v206, v206, v207
	v_cvt_pk_bf16_f32 v207, v208, v209
	v_cvt_pk_bf16_f32 v208, v210, v211
	v_cvt_pk_bf16_f32 v209, v212, v213
	global_store_dwordx4 v[18:19], v[206:209], off
	v_lshl_add_u64 v[18:19], v[18:19], 0, s[92:93]
	s_nop 0
	global_load_dwordx4 v[206:209], v[16:17], off offset:-16
	global_load_dwordx4 v[210:213], v[16:17], off
	v_lshl_add_u64 v[16:17], v[16:17], 0, s[90:91]
	s_waitcnt vmcnt(21)
	v_cvt_pk_bf16_f32 v110, v110, v111
	v_cvt_pk_bf16_f32 v111, v112, v113
	v_cvt_pk_bf16_f32 v112, v114, v115
	v_cvt_pk_bf16_f32 v113, v116, v117
	global_store_dwordx4 v[18:19], v[110:113], off
	v_lshl_add_u64 v[18:19], v[18:19], 0, s[92:93]
	s_nop 0
	global_load_dwordx4 v[110:113], v[16:17], off offset:-16
	global_load_dwordx4 v[114:117], v[16:17], off
	v_lshl_add_u64 v[16:17], v[16:17], 0, s[90:91]
	s_waitcnt vmcnt(21)
	v_cvt_pk_bf16_f32 v24, v24, v25
	v_cvt_pk_bf16_f32 v25, v26, v27
	v_cvt_pk_bf16_f32 v26, v28, v29
	v_cvt_pk_bf16_f32 v27, v30, v31
	global_store_dwordx4 v[18:19], v[24:27], off
	v_lshl_add_u64 v[18:19], v[18:19], 0, s[92:93]
	s_waitcnt vmcnt(19)
	v_cvt_pk_bf16_f32 v138, v138, v139
	v_cvt_pk_bf16_f32 v139, v140, v141
	v_cvt_pk_bf16_f32 v140, v142, v143
	v_cvt_pk_bf16_f32 v141, v144, v145
	global_store_dwordx4 v[18:19], v[138:141], off
	v_lshl_add_u64 v[18:19], v[18:19], 0, s[92:93]
	s_waitcnt vmcnt(17)
	v_cvt_pk_bf16_f32 v146, v146, v147
	v_cvt_pk_bf16_f32 v147, v148, v149
	v_cvt_pk_bf16_f32 v148, v150, v151
	v_cvt_pk_bf16_f32 v149, v152, v153
	global_store_dwordx4 v[18:19], v[146:149], off
	v_lshl_add_u64 v[18:19], v[18:19], 0, s[92:93]
	s_waitcnt vmcnt(15)
	v_cvt_pk_bf16_f32 v154, v154, v155
	v_cvt_pk_bf16_f32 v155, v156, v157
	v_cvt_pk_bf16_f32 v156, v158, v159
	v_cvt_pk_bf16_f32 v157, v160, v161
	global_store_dwordx4 v[18:19], v[154:157], off
	v_lshl_add_u64 v[18:19], v[18:19], 0, s[92:93]
	s_waitcnt vmcnt(13)
	v_cvt_pk_bf16_f32 v162, v162, v163
	v_cvt_pk_bf16_f32 v163, v164, v165
	v_cvt_pk_bf16_f32 v164, v194, v195
	v_cvt_pk_bf16_f32 v165, v196, v197
	global_store_dwordx4 v[18:19], v[162:165], off
	v_lshl_add_u64 v[18:19], v[18:19], 0, s[92:93]
	s_waitcnt vmcnt(11)
	v_cvt_pk_bf16_f32 v198, v198, v199
	v_cvt_pk_bf16_f32 v199, v200, v201
	v_cvt_pk_bf16_f32 v200, v202, v203
	v_cvt_pk_bf16_f32 v201, v204, v205
	global_store_dwordx4 v[18:19], v[198:201], off
	v_lshl_add_u64 v[18:19], v[18:19], 0, s[92:93]
	s_waitcnt vmcnt(9)
	v_cvt_pk_bf16_f32 v206, v206, v207
	v_cvt_pk_bf16_f32 v207, v208, v209
	v_cvt_pk_bf16_f32 v208, v210, v211
	v_cvt_pk_bf16_f32 v209, v212, v213
	global_store_dwordx4 v[18:19], v[206:209], off
	v_lshl_add_u64 v[18:19], v[18:19], 0, s[92:93]
	s_waitcnt vmcnt(7)
	v_cvt_pk_bf16_f32 v110, v110, v111
	v_cvt_pk_bf16_f32 v111, v112, v113
	v_cvt_pk_bf16_f32 v112, v114, v115
	v_cvt_pk_bf16_f32 v113, v116, v117
	global_store_dwordx4 v[18:19], v[110:113], off
	v_lshl_add_u64 v[18:19], v[18:19], 0, s[92:93]
	s_branch .LBB0_77
